# scan phase: unit to (chain, slice) mapping changed so the four slices of a chain run on one XCD and share the K tile in L2
# speedup vs baseline: 1.0025x; 1.0020x over previous
; #define LAS __attribute__((address_space(3)))
; __device__ __forceinline__ int scan_chunk(int s, int dir, int b) { if (s < 2) return 256 + 2 * b + (dir ? 1 - s : s); const int li = s - 2; return 32 * b + (dir ? 31 - li : li); }
; __device__ __forceinline__ float wave_sum(float v) {
; #pragma unroll
;     for (int o = 32; o; o >>= 1) v += __shfl_xor(v, o);
;     return v; }
; __device__ __forceinline__ float wave_max(float v) {
; #pragma unroll
;     for (int o = 32; o; o >>= 1) v = fmaxf(v, __shfl_xor(v, o));
;     return v; }
; __device__ __forceinline__ float wave_scan_sum(float v, int lane) {
; #pragma unroll
;     for (int o = 1; o < 64; o <<= 1) { const float t = __shfl_up(v, o); if (lane >= o) v += t; }
;     return v; }
; __device__ __forceinline__ float wave_scan_max(float v, int lane) {
; #pragma unroll
;     for (int o = 1; o < 64; o <<= 1) { const float t = __shfl_up(v, o); if (lane >= o) v = fmaxf(v, t); }
;     return v; }
; __device__ __forceinline__ void scan_phase(const Params& p, LAS unsigned char* lds) {
;     LAS float* wls = (LAS float*)(lds + 113152);
;     LAS float* scs = (LAS float*)(lds + 113152 + 17408);
;     const int t = threadIdx.x, wid = t >> 6, lane = t & 63, fr = lane & 15, fq = lane >> 4;
;     bf16_t* CP = (bf16_t*)(p.ws + WS_XN); float* MP = (float*)(p.ws + WS_MPREV);
;     const float* G = (const float*)(p.ws + WS_G);
;     for (int u = blockIdx.x; u < 256; u += gridDim.x) {
;         const int chain = u >> 2, slice = u & 3, dir = chain & 1, bh = chain >> 1, h = bh & 3, b = bh >> 2;
;         u32x4 kreg[4], vreg[2];
;         scan_issue(p, 0, dir, b, h, slice, kreg, vreg);
;         for (int s = wid; s < 34; s += 8) {
;             const int ck = scan_chunk(s, dir, b);
;             const int p0 = 2 * lane, t0 = dir ? 127 - p0 : p0, t1 = dir ? 126 - p0 : p0 + 1;
;             const float* g = G + (size_t)ck * 128 * 16 + dir * 8 + h;
;             const float gi0 = g[t0 * 16], gi1 = g[t1 * 16], gf0 = g[t0 * 16 + 4], gf1 = g[t1 * 16 + 4];
.LBB0_1390:
	s_cmp_lt_i32 s76, 8
	s_cselect_b64 s[0:1], -1, 0
	s_cmp_gt_i32 s77, 7
	s_cselect_b64 s[4:5], -1, 0
	s_and_b64 s[0:1], s[0:1], s[4:5]
	s_andn2_b64 vcc, exec, s[0:1]
	s_cbranch_vccnz .LBB0_1482
	v_writelane_b32 v254, s71, 35
	v_writelane_b32 v254, s96, 36
	s_cmpk_gt_i32 s2, 0xff
	s_nop 0
	v_writelane_b32 v254, s97, 37
	s_cbranch_scc1 .LBB0_1428
	v_bfe_u32 v5, v140, 4, 2
	v_lshlrev_b32_e32 v7, 4, v244
	v_lshl_or_b32 v6, v5, 2, v7
	v_lshlrev_b32_e32 v71, 3, v5
	v_mbcnt_lo_u32_b32 v5, -1, 0
	v_mbcnt_hi_u32_b32 v5, -1, v5
	v_and_b32_e32 v9, 64, v5
	v_add_u32_e32 v10, -1, v5
	v_cmp_lt_i32_e32 vcc, v10, v9
	s_add_u32 s3, s74, 0xa1a2000
	s_addc_u32 s33, s75, 0
	v_cndmask_b32_e32 v10, v10, v5, vcc
	v_lshlrev_b32_e32 v72, 2, v10
	v_add_u32_e32 v10, -2, v5
	v_cmp_lt_i32_e32 vcc, v10, v9
	s_add_u32 s36, s74, 0x129a2000
	s_addc_u32 s37, s75, 0
	v_cndmask_b32_e32 v10, v10, v5, vcc
	v_lshlrev_b32_e32 v73, 2, v10
	v_add_u32_e32 v10, -4, v5
	v_cmp_lt_i32_e32 vcc, v10, v9
	v_lshlrev_b32_e32 v4, 3, v140
	s_add_u32 s38, s74, 0x271a4000
	v_cndmask_b32_e32 v10, v10, v5, vcc
	v_lshlrev_b32_e32 v74, 2, v10
	v_add_u32_e32 v10, -8, v5
	v_cmp_lt_i32_e32 vcc, v10, v9
	v_and_b32_e32 v48, 0x78, v4
	s_addc_u32 s39, s75, 0
	v_cndmask_b32_e32 v10, v10, v5, vcc
	v_lshlrev_b32_e32 v75, 2, v10
	v_add_u32_e32 v10, -16, v5
	v_cmp_lt_i32_e32 vcc, v10, v9
	s_add_i32 s19, 0, 0x1bc00
	v_and_b32_e32 v1, 15, v140
	v_cndmask_b32_e32 v10, v10, v5, vcc
	v_lshlrev_b32_e32 v76, 2, v10
	v_subrev_u32_e32 v10, 32, v5
	v_cmp_lt_i32_e32 vcc, v10, v9
	v_add_u32_e32 v9, 64, v9
	v_and_b32_e32 v3, 63, v140
	v_cndmask_b32_e32 v10, v10, v5, vcc
	v_lshlrev_b32_e32 v77, 2, v10
	v_bfrev_b32_e32 v10, 0.5
	v_lshl_or_b32 v78, v5, 2, v10
	v_xor_b32_e32 v10, 32, v5
	v_cmp_lt_i32_e32 vcc, v10, v9
	v_lshlrev_b32_e32 v50, 1, v48
	v_mov_b32_e32 v51, 0
	v_cndmask_b32_e32 v10, v5, v10, vcc
	v_lshlrev_b32_e32 v79, 2, v10
	v_xor_b32_e32 v10, 16, v5
	v_cmp_lt_i32_e32 vcc, v10, v9
	v_lshlrev_b32_e32 v49, 1, v3
	v_cmp_eq_u32_e64 s[0:1], 0, v3
	v_cndmask_b32_e32 v10, v5, v10, vcc
	v_lshlrev_b32_e32 v80, 2, v10
	v_xor_b32_e32 v10, 8, v5
	v_cmp_lt_i32_e32 vcc, v10, v9
	v_cmp_gt_u32_e64 s[4:5], 2, v3
	v_cmp_gt_u32_e64 s[6:7], 4, v3
	v_cndmask_b32_e32 v10, v5, v10, vcc
	v_lshlrev_b32_e32 v81, 2, v10
	v_xor_b32_e32 v10, 4, v5
	v_cmp_lt_i32_e32 vcc, v10, v9
	v_cmp_gt_u32_e64 s[8:9], 8, v3
	v_cmp_gt_u32_e64 s[10:11], 16, v3
	v_cndmask_b32_e32 v10, v5, v10, vcc
	v_lshlrev_b32_e32 v82, 2, v10
	v_xor_b32_e32 v10, 2, v5
	v_cmp_lt_i32_e32 vcc, v10, v9
	v_cmp_gt_u32_e64 s[12:13], 32, v3
	v_lshrrev_b32_e32 v3, 4, v140
	v_cndmask_b32_e32 v10, v5, v10, vcc
	v_lshlrev_b32_e32 v83, 2, v10
	v_xor_b32_e32 v10, 1, v5
	v_cmp_lt_i32_e32 vcc, v10, v9
	v_add_u32_e32 v9, 0x600, v140
	v_lshrrev_b32_e32 v9, 4, v9
	v_cndmask_b32_e32 v5, v5, v10, vcc
	v_lshlrev_b32_e32 v84, 2, v5
	v_add_u32_e32 v5, 0x200, v140
	v_mul_u32_u24_e32 v87, 0x110, v9
	v_lshlrev_b32_e32 v9, 2, v48
	v_lshrrev_b32_e32 v5, 4, v5
	v_and_b32_e32 v10, 48, v140
	v_add_u32_e32 v93, s19, v9
	s_add_i32 s19, 0, 0x16500
	s_movk_i32 s18, 0x110
	v_or_b32_e32 v8, v7, v1
	v_add_u32_e32 v85, 0, v50
	v_mul_u32_u24_e32 v86, 0x110, v5
	v_mov_b32_e32 v5, 0x4400
	s_add_i32 s20, 0, 0x1ba00
	v_add_u32_e32 v90, 0, v10
	v_add_u32_e32 v94, s19, v50
	v_mul_u32_u24_e32 v69, 0x110, v3
	v_mul_u32_u24_e32 v70, 0x110, v8
	v_mad_u32_u24 v5, v3, s18, v5
	v_add_u32_e32 v88, s20, v9
	v_mad_u32_u24 v89, v3, s18, v85
	v_mad_u32_u24 v91, v8, s18, v90
	v_mad_u32_u24 v95, v3, s18, v94
	v_add_u32_e32 v3, s19, v10
	v_lshl_add_u64 v[8:9], s[74:75], 0, v[50:51]
	s_mov_b64 s[18:19], 0x34fa4000
	s_add_u32 s26, s74, 0x371a4000
	v_lshl_add_u64 v[54:55], v[8:9], 0, s[18:19]
	s_addc_u32 s27, s75, 0
	s_add_i32 s18, 0, 0x1fe18
	v_writelane_b32 v254, s18, 38
	s_add_i32 s18, 0, 0x1fe28
	v_writelane_b32 v254, s18, 40
	s_add_i32 s18, 0, 0x1fe20
	v_writelane_b32 v254, s18, 42
; #define LAS __attribute__((address_space(3)))
; __device__ __forceinline__ void scan_phase(const Params& p, LAS unsigned char* lds) {
;     LAS float* wls = (LAS float*)(lds + 113152);
;     LAS float* scs = (LAS float*)(lds + 113152 + 17408);
;     const int t = threadIdx.x, wid = t >> 6, lane = t & 63, fr = lane & 15, fq = lane >> 4;
;     bf16_t* CP = (bf16_t*)(p.ws + WS_XN); float* MP = (float*)(p.ws + WS_MPREV);
;     const float* G = (const float*)(p.ws + WS_G);
;     for (int u = blockIdx.x; u < 256; u += gridDim.x) {
;         const int chain = u >> 2, slice = u & 3, dir = chain & 1, bh = chain >> 1, h = bh & 3, b = bh >> 2;
	s_add_i32 s18, 0, 0x1fe38
	v_writelane_b32 v254, s18, 44
	s_add_i32 s18, 0, 0x1fe30
	v_writelane_b32 v254, s18, 46
	s_add_i32 s18, 0, 0x1fe48
	v_writelane_b32 v254, s18, 48
	s_add_i32 s18, 0, 0x1fe40
	v_writelane_b32 v254, s18, 50
	s_add_i32 s18, 0, 0x1fe58
	v_writelane_b32 v254, s18, 52
	s_add_i32 s18, 0, 0x1fe50
	v_writelane_b32 v254, s18, 54
	s_add_i32 s18, 0, 0x1fe68
	v_writelane_b32 v254, s18, 56
	s_add_i32 s18, 0, 0x1fe60
	v_writelane_b32 v254, s18, 58
	s_add_i32 s18, 0, 0x1fe78
	v_writelane_b32 v254, s18, 60
	s_add_i32 s18, 0, 0x1fe70
	v_writelane_b32 v254, s18, 62
	s_add_i32 s18, 0, 0x1fe88
	v_writelane_b32 v255, s18, 0
	s_add_i32 s18, 0, 0x1fe80
	v_writelane_b32 v255, s18, 2
	s_add_i32 s18, 0, 0x1fe98
	v_writelane_b32 v255, s18, 4
	s_add_i32 s18, 0, 0x1fe90
	v_writelane_b32 v255, s18, 6
	s_add_i32 s18, 0, 0x1fea8
	v_writelane_b32 v255, s18, 8
	s_add_i32 s18, 0, 0x1fea0
	v_writelane_b32 v255, s18, 10
	s_add_i32 s18, 0, 0x1feb8
	v_writelane_b32 v255, s18, 12
	s_add_i32 s18, 0, 0x1feb0
	v_writelane_b32 v255, s18, 14
	s_add_i32 s18, 0, 0x1fec8
	v_writelane_b32 v255, s18, 16
	s_add_i32 s18, 0, 0x1fec0
	v_writelane_b32 v255, s18, 18
	s_add_i32 s18, 0, 0x1fed8
	v_add_u32_e32 v7, 0, v7
	v_writelane_b32 v255, s18, 20
	s_add_i32 s18, 0, 0x1fed0
	v_add_u32_e32 v96, 0x1fe0c, v7
	v_lshrrev_b32_e32 v7, 3, v140
	v_writelane_b32 v255, s18, 22
	s_add_i32 s18, 0, 0x1fee8
	v_and_b32_e32 v0, 0x1f80, v4
	v_add_u32_e32 v2, 0x1000, v4
	v_add_u32_e32 v4, 0x3000, v4
	v_and_b32_e32 v7, 0x70, v7
	v_writelane_b32 v255, s18, 24
	s_add_i32 s18, 0, 0x1fee0
	v_and_b32_e32 v2, 0x3f80, v2
	v_and_b32_e32 v4, 0x7f80, v4
	s_movk_i32 s14, 0x100
	v_lshlrev_b32_e32 v52, 7, v1
	v_mul_u32_u24_e32 v92, 0x110, v1
	v_add_u32_e32 v7, 0, v7
	v_lshl_add_u32 v1, v1, 5, 0
	v_writelane_b32 v255, s18, 26
	s_add_i32 s18, 0, 0x20014
	s_movk_i32 s40, 0x1000
	v_xor_b32_e32 v53, 0x7f, v49
	v_xor_b32_e32 v67, 0x7e, v49
	v_or_b32_e32 v68, 1, v49
	s_mov_b32 s25, 0
	v_cmp_gt_u32_e64 s[14:15], s14, v140
	v_cmp_gt_u32_e64 s[16:17], 16, v140
	v_lshl_add_u64 v[56:57], s[26:27], 0, v[50:51]
	v_lshl_add_u32 v97, v244, 9, s20
	v_sub_u32_e32 v98, 0, v244
	v_add_u32_e32 v99, 0xfffffe00, v140
	v_add_u32_e32 v100, 0x1fe08, v7
	v_lshl_add_u32 v101, v140, 2, s20
	v_add_u32_e32 v102, 0x1be00, v1
	v_lshlrev_b32_e32 v58, 1, v0
	v_lshlrev_b32_e32 v60, 1, v2
	s_movk_i32 s41, 0x4000
	v_lshlrev_b32_e32 v62, 1, v4
	v_lshlrev_b32_e32 v64, 1, v48
	s_add_i32 s42, 0, 0x1fe00
	s_add_i32 s44, 0, 0x1fe10
	s_add_i32 s81, 0, 0x1fef8
	s_add_i32 s82, 0, 0x1fef0
	s_add_i32 s83, 0, 0x1ff08
	s_add_i32 s84, 0, 0x1ff00
	s_add_i32 s85, 0, 0x1ff18
	s_add_i32 s86, 0, 0x1ff10
	s_add_i32 s87, 0, 0x1ff28
	s_add_i32 s88, 0, 0x1ff20
	s_add_i32 s89, 0, 0x1ff38
	s_add_i32 s90, 0, 0x1ff30
	s_add_i32 s91, 0, 0x1ff48
	s_add_i32 s92, 0, 0x1ff40
	s_add_i32 s93, 0, 0x1ff58
	s_add_i32 s94, 0, 0x1ff50
	s_add_i32 s95, 0, 0x1ff68
	s_add_i32 s96, 0, 0x1ff60
	s_add_i32 s97, 0, 0x1ff78
	s_add_i32 s22, 0, 0x1ff70
	s_add_i32 s23, 0, 0x1ff88
	s_add_i32 s43, 0, 0x1ff80
	s_add_i32 s45, 0, 0x1ff98
	s_add_i32 s46, 0, 0x1ff90
	s_add_i32 s47, 0, 0x1ffa8
	s_add_i32 s48, 0, 0x1ffa0
	s_add_i32 s49, 0, 0x1ffb8
	s_add_i32 s50, 0, 0x1ffb0
	s_add_i32 s51, 0, 0x1ffc8
	s_add_i32 s52, 0, 0x1ffc0
	s_add_i32 s53, 0, 0x1ffd8
	s_add_i32 s54, 0, 0x1ffd0
	s_add_i32 s55, 0, 0x1ffe8
	s_add_i32 s56, 0, 0x1ffe0
	s_add_i32 s57, 0, 0x1fff8
	s_add_i32 s58, 0, 0x1fff0
	s_add_i32 s59, 0, 0x20008
	s_add_i32 s60, 0, 0x20000
	s_add_i32 s61, 0, 0x20018
	s_add_i32 s62, 0, 0x20010
	v_add_u32_e32 v103, v3, v92
	s_add_i32 s63, 0, 0x1fe24
	v_lshlrev_b32_e32 v50, 1, v6
	v_writelane_b32 v255, s18, 28
	v_add_u32_e32 v104, v85, v5
	s_and_b32 s98, s2, 7
	s_lshr_b32 s99, s2, 3
	s_and_b32 s100, s99, 3
	s_lshr_b32 s99, s99, 2
	s_lshl_b32 s99, s99, 3
	s_add_i32 s98, s98, s99
	s_lshl_b32 s98, s98, 2
	s_or_b32 s64, s98, s100
	s_branch .LBB0_1395
